# AM (intra-chunk attention matrix) stored fragment-contiguous: the scan phase's two A-operand loads per chunk become 1 KiB-contiguous
# baseline (speedup 1.0000x reference)
.LBB0_195:
	s_andn2_b64 vcc, exec, s[0:1]
	s_cbranch_vccnz .LBB0_205
	v_readfirstlane_b32 s0, v184
	v_readfirstlane_b32 s1, v185
	v_mov_b32_e32 v152, v189
	s_andn2_b64 vcc, exec, s[68:69]
	s_cbranch_vccnz .LBB0_205
	v_and_b32_e32 v200, 31, v152
	v_and_b32_e32 v4, 0xffffffc0, v152
	v_lshlrev_b32_e32 v186, 11, v200
	v_ashrrev_i32_e32 v5, 31, v4
	s_waitcnt lgkmcnt(0)
	v_bfe_u32 v21, v152, 5, 1
	v_lshl_add_u64 v[2:3], s[0:1], 0, v[186:187]
	v_lshlrev_b64 v[6:7], 1, v[4:5]
	v_ashrrev_i32_e32 v0, 6, v152
	v_lshl_add_u64 v[2:3], v[2:3], 0, v[6:7]
	v_lshlrev_b32_e32 v154, 4, v21
	v_mov_b32_e32 v155, v187
	v_lshl_add_u64 v[2:3], v[2:3], 0, v[154:155]
	s_mov_b64 s[2:3], 0xc000000
	s_waitcnt vmcnt(1)
	v_lshlrev_b32_e32 v10, 4, v0
	v_lshl_add_u64 v[156:157], v[2:3], 0, s[2:3]
	v_lshlrev_b32_e32 v2, 7, v200
	v_mov_b32_e32 v3, v187
	v_ashrrev_i32_e32 v11, 31, v10
	v_lshl_add_u64 v[8:9], s[0:1], 0, v[2:3]
	v_lshlrev_b64 v[10:11], 1, v[10:11]
	v_lshl_add_u64 v[8:9], v[8:9], 0, v[10:11]
	v_lshl_add_u64 v[8:9], v[8:9], 0, v[154:155]
	s_mov_b64 s[2:3], 0xe000000
	v_lshl_add_u64 v[158:159], v[8:9], 0, s[2:3]
	v_lshrrev_b32_e32 v8, 6, v152
	v_lshlrev_b32_e32 v8, 11, v8
	v_and_b32_e32 v9, 63, v152
	v_lshl_or_b32 v8, v9, 4, v8
	v_mov_b32_e32 v9, 0
	v_lshl_add_u64 v[158:159], s[0:1], 0, v[8:9]
	v_lshl_add_u64 v[158:159], v[158:159], 0, s[2:3]
	v_lshl_add_u64 v[8:9], s[0:1], 0, v[154:155]
	s_mov_b64 s[2:3], 0x8000000
	v_lshl_add_u64 v[160:161], v[8:9], 0, s[2:3]
	s_mov_b64 s[2:3], 0xd000000
	v_lshl_add_u64 v[162:163], v[8:9], 0, s[2:3]
	v_ashrrev_i32_e32 v8, 2, v152
	v_ashrrev_i32_e32 v9, 31, v8
	v_lshlrev_b64 v[12:13], 12, v[8:9]
	v_lshl_add_u64 v[14:15], s[0:1], 0, v[12:13]
	s_mov_b64 s[2:3], 0x6000000
	v_lshlrev_b32_e32 v1, 3, v152
	v_lshl_add_u64 v[164:165], v[14:15], 0, s[2:3]
	v_and_b32_e32 v14, 24, v1
	v_ashrrev_i32_e32 v1, 31, v0
	v_and_b32_e32 v20, 63, v152
	v_lshlrev_b64 v[16:17], 13, v[0:1]
	v_lshl_add_u64 v[18:19], v[4:5], 2, s[0:1]
	v_lshl_add_u64 v[18:19], v[18:19], 0, v[154:155]
	s_mov_b64 s[2:3], 0x5000000
	v_lshlrev_b32_e32 v1, 2, v14
	v_cmp_eq_u32_e64 s[12:13], 1, v0
	v_cmp_eq_u32_e64 s[14:15], 2, v0
	v_lshlrev_b32_e32 v0, 7, v4
	v_lshl_or_b32 v16, v20, 2, v16
	v_lshl_add_u64 v[166:167], v[18:19], 0, s[2:3]
	v_lshl_or_b32 v202, v4, 2, v154
	v_lshl_or_b32 v203, v8, 7, v1
	v_lshl_or_b32 v4, v21, 9, v0
	v_lshl_add_u64 v[0:1], s[0:1], 0, v[16:17]
	s_mov_b64 s[2:3], 0x4001f00
	v_lshl_add_u64 v[168:169], v[0:1], 0, s[2:3]
	v_and_b32_e32 v0, 3, v152
	v_or_b32_e32 v186, v186, v154
	s_add_u32 s20, s0, 0x3d80000
	v_ashrrev_i32_e32 v153, 31, v152
	v_lshlrev_b32_e32 v3, 2, v200
	v_lshl_or_b32 v12, v0, 4, v12
	s_mov_b64 s[2:3], 0x6000008
	v_lshl_add_u64 v[174:175], v[186:187], 0, v[6:7]
	v_or_b32_e32 v186, v2, v154
	v_and_b32_e32 v201, 0xffffffdf, v152
	s_addc_u32 s21, s1, 0
	v_lshlrev_b32_e32 v155, 2, v152
	v_cmp_gt_u32_e64 s[10:11], 64, v152
	v_lshl_add_u64 v[170:171], v[152:153], 2, v[190:191]
	v_lshl_add_u64 v[172:173], v[12:13], 0, s[2:3]
	v_lshrrev_b32_e32 v176, 6, v152
	v_lshlrev_b32_e32 v176, 11, v176
	v_and_b32_e32 v177, 63, v152
	v_lshl_or_b32 v176, v177, 4, v176
	v_mov_b32_e32 v177, 0
	v_or_b32_e32 v178, 0x80000c0, v154
	v_mov_b32_e32 v179, v187
	v_lshlrev_b32_e32 v186, 1, v14
	v_add_u32_e32 v204, v3, v4
	s_mov_b32 s22, s50
	s_mov_b32 s23, s50

.LBB0_202:
	s_lshr_b32 s30, s23, 6
	s_lshl_b32 s30, s30, 19
	s_bfe_u32 s31, s23, 0x20004
	s_lshl_b32 s31, s31, 22
	s_or_b32 s30, s30, s31
	s_lshr_b32 s32, s23, 6
	s_lshl_b32 s32, s32, 20
	s_bfe_u32 s31, s23, 0x20004
	s_lshl_b32 s31, s31, 23
	s_or_b32 s32, s32, s31
	s_and_b32 s31, s23, 15
	s_lshl_b32 s31, s31, 12
	s_or_b32 s32, s32, s31
	s_lshr_b32 s6, s23, 4
	v_lshlrev_b32_e32 v34, 14, v200
	s_and_b32 s6, s6, 3
	v_lshl_or_b32 v34, s3, 23, v34
	s_lshl_b32 s3, s23, 5
	s_lshl_b32 s66, s6, 9
	s_and_b32 s24, s3, 0x1e0
	s_or_b32 s3, s24, s66
	s_lshl_b32 s18, s2, 4
	s_lshl_b32 s2, s2, 10
	v_or_b32_e32 v42, s3, v200
	s_ashr_i32 s19, s18, 31
	s_ashr_i32 s3, s2, 31
	s_lshl_b32 s25, s6, 10
	s_lshl_b32 s28, s5, 6
	v_add_u32_e32 v32, s4, v201
	s_lshl_b32 s4, s6, 13
	v_lshl_or_b32 v34, s5, 19, v34
	v_lshl_add_u32 v36, s6, 8, v201
	s_mov_b32 s5, s67
	s_lshl_b64 s[16:17], s[18:19], 17
	s_lshl_b64 s[6:7], s[18:19], 15
	s_lshl_b64 s[8:9], s[2:3], 1
	s_lshl_b64 s[2:3], s[18:19], 18
	s_lshl_b64 s[18:19], s[18:19], 12
	v_lshl_add_u64 v[40:41], v[158:159], 0, s[4:5]
	s_add_u32 s5, s20, s18
	v_lshl_add_u64 v[38:39], v[156:157], 0, s[66:67]
	s_addc_u32 s27, s21, s19
	v_lshl_add_u64 v[38:39], v[38:39], 0, s[16:17]
	s_add_u32 s26, s5, s25
	s_mov_b32 s5, 0x10000
	v_ashrrev_i32_e32 v37, 31, v36
	v_lshl_add_u64 v[40:41], v[40:41], 0, s[6:7]
	v_lshrrev_b32_e32 v214, 6, v152
	v_and_b32_e32 v215, 63, v152
	v_lshlrev_b32_e32 v214, 13, v214
	v_lshl_or_b32 v214, v215, 4, v214
	v_add_u32_e32 v194, s30, v214
	v_mov_b32_e32 v195, 0
	v_lshl_add_u64 v[38:39], s[0:1], 0, v[194:195]
	v_add_co_u32_e32 v38, vcc, 0xe801000, v38
	s_nop 1
	v_addc_co_u32_e32 v39, vcc, 0, v39, vcc
	global_load_dwordx4 v[96:99], v[38:39], off offset:-4096
	global_load_dwordx4 v[88:91], v[38:39], off offset:-3072
	global_load_dwordx4 v[80:83], v[38:39], off offset:-2048
	global_load_dwordx4 v[72:75], v[38:39], off offset:-1024
	global_load_dwordx4 v[64:67], v[40:41], off
	v_lshlrev_b64 v[36:37], 14, v[36:37]
	v_lshlrev_b32_e32 v42, 14, v42
	v_mov_b32_e32 v43, v187
	v_lshl_add_u64 v[36:37], v[162:163], 0, v[36:37]
	global_load_dwordx4 v[100:103], v[38:39], off
	global_load_dwordx4 v[92:95], v[38:39], off offset:1024
	global_load_dwordx4 v[84:87], v[38:39], off offset:2048
	global_load_dwordx4 v[76:79], v[38:39], off offset:3072
	v_add_co_u32_e32 v38, vcc, 0x400, v40
	v_lshl_add_u64 v[42:43], v[160:161], 0, v[42:43]
	s_nop 0
	v_addc_co_u32_e32 v39, vcc, 0, v41, vcc
	v_lshl_add_u64 v[36:37], v[36:37], 0, s[8:9]
	v_lshlrev_b32_e32 v218, 4, v215
	v_add_u32_e32 v218, s32, v218
	v_mov_b32_e32 v219, 0
	v_lshl_add_u64 v[42:43], s[0:1], 0, v[218:219]
	v_add_co_u32_e32 v42, vcc, 0x8000000, v42
	s_nop 1
	v_addc_co_u32_e32 v43, vcc, 0, v43, vcc
	global_load_dwordx4 v[68:71], v[38:39], off
	global_load_dwordx4 v[108:111], v[42:43], off
	global_load_dwordx4 v[104:107], v[42:43], off offset:1024
	global_load_dwordx4 v[112:115], v[42:43], off offset:2048
	global_load_dwordx4 v[116:119], v[42:43], off offset:3072
	v_lshrrev_b32_e32 v214, 6, v152
	v_and_b32_e32 v215, 63, v152
	v_lshlrev_b32_e32 v214, 13, v214
	v_lshl_or_b32 v214, v215, 4, v214
	v_add_u32_e32 v194, s30, v214
	v_mov_b32_e32 v195, 0
	v_lshl_add_u64 v[36:37], s[0:1], 0, v[194:195]
	v_add_co_u32_e32 v36, vcc, 0xd001000, v36
	s_nop 1
	v_addc_co_u32_e32 v37, vcc, 0, v37, vcc
	global_load_dwordx4 v[148:151], v[36:37], off offset:-4096
	global_load_dwordx4 v[144:147], v[36:37], off offset:-3072
	global_load_dwordx4 v[140:143], v[36:37], off offset:-2048
	global_load_dwordx4 v[136:139], v[36:37], off offset:-1024
	s_addc_u32 s27, s27, 0
	s_nop 0
	global_load_dwordx4 v[132:135], v[36:37], off
	global_load_dwordx4 v[128:131], v[36:37], off offset:1024
	global_load_dwordx4 v[124:127], v[36:37], off offset:2048
	global_load_dwordx4 v[120:123], v[36:37], off offset:3072
	v_lshl_add_u64 v[36:37], v[152:153], 2, s[26:27]
	s_barrier
	global_load_dword v36, v[36:37], off
	v_ashrrev_i32_e32 v33, 31, v32
	v_lshlrev_b64 v[32:33], 14, v[32:33]
	s_or_b32 s18, s18, s25
	v_mov_b32_e32 v35, v187
	v_lshl_add_u64 v[180:181], s[18:19], 0, v[170:171]
	s_or_b32 s18, s28, s25
	v_or_b32_e32 v32, v154, v32
	s_or_b32 s18, s2, s18
	s_mov_b32 s19, s3
	s_or_b32 s16, s16, s66
	s_or_b32 s6, s6, s4
	v_lshl_add_u64 v[32:33], v[178:179], 0, v[34:35]
	s_mov_b32 s5, 0
	v_lshl_add_u64 v[182:183], s[18:19], 0, v[172:173]
	v_lshl_add_u64 v[192:193], s[16:17], 0, v[174:175]
	v_lshl_add_u64 v[196:197], s[6:7], 0, v[176:177]
	v_add_u32_e32 v198, 0x8010000, v218
	v_mov_b32_e32 v199, 0
	s_mov_b64 s[30:31], 0x10000
	s_waitcnt vmcnt(0)
	ds_write_b32 v155, v36 offset:32768
	s_waitcnt lgkmcnt(0)
	s_barrier
.LBB0_203:
	v_lshl_add_u64 v[32:33], s[0:1], 0, v[180:181]
	global_load_dword v205, v[32:33], off
	v_cvt_pk_bf16_f32 v32, v16, v17
	v_cvt_pk_bf16_f32 v33, v18, v19
	v_cvt_pk_bf16_f32 v34, v20, v21
	v_cvt_pk_bf16_f32 v35, v22, v23
	s_mov_b32 s4, 0xc020000
	s_waitcnt vmcnt(10)
	v_cndmask_b32_e64 v206, v119, v115, s[14:15]
	v_mfma_f32_32x32x16_bf16 v[48:63], v[96:99], v[32:35], 0
	v_cvt_pk_bf16_f32 v96, v24, v25
	v_cvt_pk_bf16_f32 v97, v26, v27
	v_cvt_pk_bf16_f32 v98, v28, v29
	v_cvt_pk_bf16_f32 v99, v30, v31
	v_cndmask_b32_e64 v207, v118, v114, s[14:15]
	v_cndmask_b32_e64 v208, v117, v113, s[14:15]
	v_cndmask_b32_e64 v209, v116, v112, s[14:15]
	v_mfma_f32_32x32x16_bf16 v[48:63], v[88:91], v[96:99], v[48:63]
	v_cvt_pk_bf16_f32 v88, v0, v1
	v_cvt_pk_bf16_f32 v89, v2, v3
	v_cvt_pk_bf16_f32 v90, v4, v5
	v_cvt_pk_bf16_f32 v91, v6, v7
	v_cndmask_b32_e64 v210, v209, v104, s[12:13]
	v_cndmask_b32_e64 v211, v208, v105, s[12:13]
	v_cndmask_b32_e64 v207, v207, v106, s[12:13]
	v_mfma_f32_32x32x16_bf16 v[32:47], v[100:103], v[32:35], 0
	v_cndmask_b32_e64 v206, v206, v107, s[12:13]
	v_cndmask_b32_e64 v209, v206, v111, s[10:11]
	v_cndmask_b32_e64 v208, v207, v110, s[10:11]
	v_cndmask_b32_e64 v207, v211, v109, s[10:11]
	v_cndmask_b32_e64 v206, v210, v108, s[10:11]
	v_add_u32_e32 v210, 0x1800, v204
	v_add_u32_e32 v211, 0x1c00, v204
	v_mfma_f32_32x32x16_bf16 v[48:63], v[80:83], v[88:91], v[48:63]
	v_cvt_pk_bf16_f32 v80, v8, v9
	v_cvt_pk_bf16_f32 v81, v10, v11
	v_cvt_pk_bf16_f32 v82, v12, v13
	v_cvt_pk_bf16_f32 v83, v14, v15
	s_mov_b64 s[6:7], 0x8000
	v_lshl_add_u64 v[180:181], v[180:181], 0, s[86:87]
	s_waitcnt vmcnt(2)
	v_mfma_f32_32x32x16_bf16 v[16:31], v[148:151], v[108:111], v[16:31]
	v_mfma_f32_32x32x16_bf16 v[0:15], v[132:135], v[108:111], v[0:15]
	v_mfma_f32_32x32x16_bf16 v[32:47], v[92:95], v[96:99], v[32:47]
	v_mfma_f32_32x32x16_bf16 v[16:31], v[144:147], v[104:107], v[16:31]
	v_mfma_f32_32x32x16_bf16 v[0:15], v[128:131], v[104:107], v[0:15]
	v_mfma_f32_32x32x16_bf16 v[32:47], v[84:87], v[88:91], v[32:47]
	v_mfma_f32_32x32x16_bf16 v[48:63], v[72:75], v[80:83], v[48:63]
	v_mfma_f32_32x32x16_bf16 v[16:31], v[140:143], v[112:115], v[16:31]
	v_mfma_f32_32x32x16_bf16 v[0:15], v[124:127], v[112:115], v[0:15]
	v_mfma_f32_32x32x16_bf16 v[32:47], v[76:79], v[80:83], v[32:47]
	v_lshl_add_u64 v[76:77], s[0:1], 0, v[194:195]
	v_add_co_u32_e32 v216, vcc, 0xe809000, v76
	s_mov_b32 s4, 0xc030000
	s_nop 0
	v_addc_co_u32_e32 v217, vcc, 0, v77, vcc
	v_mfma_f32_32x32x16_bf16 v[48:63], v[64:67], v[206:209], v[48:63]
	v_lshl_add_u64 v[64:65], s[0:1], 0, v[196:197]
	s_mov_b32 s4, 0xe009000
	global_load_dwordx4 v[96:99], v[216:217], off offset:-4096
	global_load_dwordx4 v[88:91], v[216:217], off offset:-3072
	global_load_dwordx4 v[80:83], v[216:217], off offset:-2048
	global_load_dwordx4 v[72:75], v[216:217], off offset:-1024
	global_load_dwordx4 v[100:103], v[216:217], off
	global_load_dwordx4 v[92:95], v[216:217], off offset:1024
	global_load_dwordx4 v[84:87], v[216:217], off offset:2048
	global_load_dwordx4 v[76:79], v[216:217], off offset:3072
	v_lshl_add_u64 v[192:193], v[192:193], 0, s[58:59]
	v_mfma_f32_32x32x16_bf16 v[16:31], v[136:139], v[116:119], v[16:31]
	v_lshl_add_u64 v[196:197], v[196:197], 0, s[6:7]
	v_mfma_f32_32x32x16_bf16 v[0:15], v[120:123], v[116:119], v[0:15]
	v_lshl_add_u64 v[116:117], s[0:1], 0, v[198:199]
	v_lshl_add_u64 v[198:199], v[198:199], 0, s[30:31]
	v_mfma_f32_32x32x16_bf16 v[32:47], v[68:71], v[206:209], v[32:47]
	v_add_co_u32_e32 v68, vcc, s4, v64
	s_and_b32 s4, s5, 0x100
	s_nop 0
	v_addc_co_u32_e32 v69, vcc, 0, v65, vcc
	v_lshl_add_u32 v206, s4, 2, v202
	global_load_dwordx4 v[64:67], v[68:69], off offset:-4096
	s_nop 0
	global_load_dwordx4 v[68:71], v[68:69], off offset:-3072
	ds_read_b128 v[136:139], v206 offset:32768
	ds_read_b128 v[140:143], v206 offset:32800
	ds_read_b128 v[104:107], v206 offset:32896
	s_mov_b32 s4, 0xd080000
	s_addk_i32 s5, 0x100
	s_waitcnt lgkmcnt(2)
	v_pk_mul_f32 v[16:17], v[16:17], v[136:137]
	v_pk_mul_f32 v[18:19], v[18:19], v[138:139]
	ds_read_b128 v[136:139], v206 offset:32832
	s_waitcnt lgkmcnt(1)
	v_pk_mul_f32 v[0:1], v[0:1], v[104:105]
	v_pk_mul_f32 v[2:3], v[2:3], v[106:107]
	ds_read_b128 v[104:107], v206 offset:32928
	v_pk_mul_f32 v[20:21], v[20:21], v[140:141]
	s_waitcnt lgkmcnt(1)
	v_pk_mul_f32 v[24:25], v[24:25], v[136:137]
	v_pk_mul_f32 v[26:27], v[26:27], v[138:139]
	ds_read_b128 v[136:139], v206 offset:32864
	s_waitcnt lgkmcnt(1)
	v_pk_mul_f32 v[4:5], v[4:5], v[104:105]
	v_pk_mul_f32 v[6:7], v[6:7], v[106:107]
	ds_read_b128 v[104:107], v206 offset:32960
	v_pk_mul_f32 v[22:23], v[22:23], v[142:143]
	s_waitcnt lgkmcnt(1)
	v_pk_mul_f32 v[28:29], v[28:29], v[136:137]
	v_lshl_add_u64 v[136:137], s[0:1], 0, v[194:195]
	v_add_co_u32_e32 v212, vcc, 0xd009000, v136
	s_waitcnt lgkmcnt(0)
	v_pk_mul_f32 v[8:9], v[8:9], v[104:105]
	v_pk_mul_f32 v[10:11], v[10:11], v[106:107]
	ds_read_b128 v[104:107], v206 offset:32992
	v_addc_co_u32_e32 v213, vcc, 0, v137, vcc
	v_pk_mul_f32 v[30:31], v[30:31], v[138:139]
	s_nop 0
	s_waitcnt lgkmcnt(0)
	v_pk_mul_f32 v[12:13], v[12:13], v[104:105]
	v_pk_mul_f32 v[14:15], v[14:15], v[106:107]
	global_load_dwordx4 v[108:111], v[116:117], off
	global_load_dwordx4 v[104:107], v[116:117], off offset:1024
	global_load_dwordx4 v[112:115], v[116:117], off offset:2048
	s_nop 0
	global_load_dwordx4 v[116:119], v[116:117], off offset:3072
	s_nop 0
	global_load_dwordx4 v[120:123], v[212:213], off offset:3072
	global_load_dwordx4 v[124:127], v[212:213], off offset:2048
	global_load_dwordx4 v[128:131], v[212:213], off offset:1024
	global_load_dwordx4 v[132:135], v[212:213], off
	global_load_dwordx4 v[136:139], v[212:213], off offset:-1024
	global_load_dwordx4 v[140:143], v[212:213], off offset:-2048
	global_load_dwordx4 v[144:147], v[212:213], off offset:-3072
	global_load_dwordx4 v[148:151], v[212:213], off offset:-4096
	s_and_b32 s4, s5, 0x100
	v_lshl_add_u32 v206, s4, 2, v155
	s_waitcnt vmcnt(22)
	ds_write_b32 v206, v205 offset:32768
	ds_write2_b32 v204, v48, v49 offset1:32
	ds_write2_b32 v204, v50, v51 offset0:64 offset1:96
	v_add_u32_e32 v205, 0x400, v204
	v_add_u32_e32 v206, 0x800, v204
	v_add_u32_e32 v207, 0xc00, v204
	v_add_u32_e32 v208, 0x1000, v204
	v_add_u32_e32 v209, 0x1400, v204
	ds_write2_b32 v205, v52, v53 offset1:32
	ds_write2_b32 v205, v54, v55 offset0:64 offset1:96
	ds_write2_b32 v206, v56, v57 offset1:32
	ds_write2_b32 v206, v58, v59 offset0:64 offset1:96
	ds_write2_b32 v207, v60, v61 offset1:32
	ds_write2_b32 v207, v62, v63 offset0:64 offset1:96
	ds_write2_b32 v208, v32, v33 offset1:32
	ds_write2_b32 v208, v34, v35 offset0:64 offset1:96
	ds_write2_b32 v209, v36, v37 offset1:32
	ds_write2_b32 v209, v38, v39 offset0:64 offset1:96
	ds_write2_b32 v210, v40, v41 offset1:32
	ds_write2_b32 v210, v42, v43 offset0:64 offset1:96
	ds_write2_b32 v211, v44, v45 offset1:32
	ds_write2_b32 v211, v46, v47 offset0:64 offset1:96
	s_waitcnt lgkmcnt(0)
	s_barrier
	ds_read_b128 v[32:35], v203
	ds_read_b128 v[36:39], v203 offset:16
	ds_read_b128 v[40:43], v203 offset:8192
	ds_read_b128 v[44:47], v203 offset:16384
	ds_read_b128 v[48:51], v203 offset:24576
	v_lshl_add_u64 v[194:195], v[194:195], 0, s[6:7]
	s_cmpk_eq_i32 s5, 0xf00
	s_waitcnt lgkmcnt(2)
	v_pk_add_f32 v[32:33], v[32:33], v[40:41]
	s_waitcnt lgkmcnt(1)
	v_pk_add_f32 v[32:33], v[32:33], v[44:45]
	s_waitcnt lgkmcnt(0)
	v_pk_add_f32 v[48:49], v[32:33], v[48:49]
	v_pk_add_f32 v[32:33], v[34:35], v[42:43]
	ds_read_b128 v[40:43], v203 offset:16400
	v_pk_add_f32 v[32:33], v[32:33], v[46:47]
	ds_read_b128 v[44:47], v203 offset:24592
	v_pk_add_f32 v[50:51], v[32:33], v[50:51]
	ds_read_b128 v[32:35], v203 offset:8208
	s_waitcnt lgkmcnt(0)
	v_pk_add_f32 v[32:33], v[36:37], v[32:33]
	s_nop 0
	v_pk_add_f32 v[32:33], v[32:33], v[40:41]
	s_nop 0
	v_pk_add_f32 v[36:37], v[32:33], v[44:45]
	v_pk_add_f32 v[32:33], v[38:39], v[34:35]
	v_cvt_pk_bf16_f32 v34, v36, v37
	v_pk_add_f32 v[32:33], v[32:33], v[42:43]
	v_lshl_add_u64 v[36:37], s[0:1], 0, v[182:183]
	v_pk_add_f32 v[38:39], v[32:33], v[46:47]
	v_cvt_pk_bf16_f32 v32, v48, v49
	v_cvt_pk_bf16_f32 v33, v50, v51
	v_cvt_pk_bf16_f32 v35, v38, v39
	v_lshl_add_u64 v[182:183], v[182:183], 0, s[90:91]
	global_store_dwordx4 v[36:37], v[32:35], off offset:-8
	s_barrier
	s_cbranch_scc0 .LBB0_203
	v_cvt_pk_bf16_f32 v16, v16, v17
	v_cvt_pk_bf16_f32 v17, v18, v19
	v_cvt_pk_bf16_f32 v18, v20, v21
	v_cvt_pk_bf16_f32 v19, v22, v23
	v_cvt_pk_bf16_f32 v0, v0, v1
	v_cvt_pk_bf16_f32 v1, v2, v3
	s_waitcnt vmcnt(22)
	v_mfma_f32_32x32x16_bf16 v[48:63], v[96:99], v[16:19], 0
	v_cvt_pk_bf16_f32 v2, v4, v5
	v_cvt_pk_bf16_f32 v3, v6, v7
	v_cvt_pk_bf16_f32 v4, v8, v9
	v_cvt_pk_bf16_f32 v5, v10, v11
	v_cvt_pk_bf16_f32 v6, v12, v13
	v_cvt_pk_bf16_f32 v7, v14, v15
	s_lshl_b32 s66, s66, 1
	s_waitcnt vmcnt(18)
	v_mfma_f32_32x32x16_bf16 v[32:47], v[100:103], v[16:19], 0
	v_cvt_pk_bf16_f32 v16, v24, v25
	v_cvt_pk_bf16_f32 v17, v26, v27
	v_cvt_pk_bf16_f32 v18, v28, v29
	v_cvt_pk_bf16_f32 v19, v30, v31
	s_add_i32 s23, s23, s64
	s_add_i32 s22, s22, s64
	v_mfma_f32_32x32x16_bf16 v[48:63], v[88:91], v[16:19], v[48:63]
	s_waitcnt vmcnt(17)
	v_mfma_f32_32x32x16_bf16 v[32:47], v[92:95], v[16:19], v[32:47]
	v_mfma_f32_32x32x16_bf16 v[48:63], v[80:83], v[0:3], v[48:63]
	s_waitcnt vmcnt(16)
	v_mfma_f32_32x32x16_bf16 v[32:47], v[84:87], v[0:3], v[32:47]
	s_waitcnt vmcnt(9)
	v_cndmask_b32_e64 v0, v119, v115, s[14:15]
	v_cndmask_b32_e64 v1, v118, v114, s[14:15]
	v_cndmask_b32_e64 v2, v117, v113, s[14:15]
	v_cndmask_b32_e64 v3, v116, v112, s[14:15]
	v_cndmask_b32_e64 v8, v3, v104, s[12:13]
	v_cndmask_b32_e64 v9, v2, v105, s[12:13]
	v_cndmask_b32_e64 v1, v1, v106, s[12:13]
	v_mfma_f32_32x32x16_bf16 v[48:63], v[72:75], v[4:7], v[48:63]
	v_cndmask_b32_e64 v0, v0, v107, s[12:13]
	v_cndmask_b32_e64 v3, v0, v111, s[10:11]
	v_cndmask_b32_e64 v2, v1, v110, s[10:11]
	v_cndmask_b32_e64 v1, v9, v109, s[10:11]
	v_cndmask_b32_e64 v0, v8, v108, s[10:11]
	v_lshl_add_u64 v[8:9], v[164:165], 0, s[66:67]
	s_lshl_b32 s66, s24, 1
	v_mfma_f32_32x32x16_bf16 v[32:47], v[76:79], v[4:7], v[32:47]
	v_lshl_add_u64 v[8:9], v[8:9], 0, s[66:67]
	v_lshl_add_u64 v[8:9], v[8:9], 0, v[186:187]
	s_cmpk_gt_i32 s23, 0x1ff
	v_mfma_f32_32x32x16_bf16 v[48:63], v[64:67], v[0:3], v[48:63]
	v_lshl_add_u64 v[64:65], v[8:9], 0, s[2:3]
	ds_write_b32 v155, v187 offset:32768
	s_nop 9
	ds_write2_b32 v204, v48, v49 offset1:32
	v_mfma_f32_32x32x16_bf16 v[32:47], v[68:71], v[0:3], v[32:47]
	ds_write2_b32 v204, v50, v51 offset0:64 offset1:96
	ds_write2_b32 v205, v52, v53 offset1:32
	ds_write2_b32 v205, v54, v55 offset0:64 offset1:96
	ds_write2_b32 v206, v56, v57 offset1:32
	ds_write2_b32 v206, v58, v59 offset0:64 offset1:96
	ds_write2_b32 v207, v60, v61 offset1:32
	ds_write2_b32 v207, v62, v63 offset0:64 offset1:96
	s_nop 4
	ds_write2_b32 v208, v32, v33 offset1:32
	ds_write2_b32 v208, v34, v35 offset0:64 offset1:96
	ds_write2_b32 v209, v36, v37 offset1:32
	ds_write2_b32 v209, v38, v39 offset0:64 offset1:96
	ds_write2_b32 v210, v40, v41 offset1:32
	ds_write2_b32 v210, v42, v43 offset0:64 offset1:96
	ds_write2_b32 v211, v44, v45 offset1:32
	ds_write2_b32 v211, v46, v47 offset0:64 offset1:96
	s_waitcnt lgkmcnt(0)
	s_barrier
	ds_read_b128 v[0:3], v203 offset:8192
	ds_read_b128 v[4:7], v203
	ds_read_b128 v[8:11], v203 offset:16
	ds_read_b128 v[12:15], v203 offset:16384
	ds_read_b128 v[16:19], v203 offset:24576
	ds_read_b128 v[20:23], v203 offset:8208
	ds_read_b128 v[24:27], v203 offset:16400
	ds_read_b128 v[28:31], v203 offset:24592
	s_waitcnt lgkmcnt(6)
	v_pk_add_f32 v[0:1], v[4:5], v[0:1]
	v_pk_add_f32 v[2:3], v[6:7], v[2:3]
	s_waitcnt lgkmcnt(2)
	v_pk_add_f32 v[4:5], v[8:9], v[20:21]
	v_pk_add_f32 v[0:1], v[0:1], v[12:13]
	v_pk_add_f32 v[2:3], v[2:3], v[14:15]
	s_waitcnt lgkmcnt(1)
	v_pk_add_f32 v[4:5], v[4:5], v[24:25]
	v_pk_add_f32 v[6:7], v[10:11], v[22:23]
	v_pk_add_f32 v[0:1], v[0:1], v[16:17]
	v_pk_add_f32 v[2:3], v[2:3], v[18:19]
	s_waitcnt lgkmcnt(0)
	v_pk_add_f32 v[4:5], v[4:5], v[28:29]
	v_pk_add_f32 v[6:7], v[6:7], v[26:27]
	v_cvt_pk_bf16_f32 v0, v0, v1
	v_pk_add_f32 v[6:7], v[6:7], v[30:31]
	v_cvt_pk_bf16_f32 v1, v2, v3
	v_cvt_pk_bf16_f32 v2, v4, v5
	v_add_co_u32_e32 v4, vcc, 0x3c0000, v64
	v_cvt_pk_bf16_f32 v3, v6, v7
	s_nop 0
	v_addc_co_u32_e32 v5, vcc, 0, v65, vcc
	global_store_dwordx4 v[4:5], v[0:3], off
	s_barrier
	s_cbranch_scc0 .LBB0_198

.LBB0_220:
	s_or_b64 exec, exec, s[2:3]
	s_andn2_b64 vcc, exec, s[68:69]
	s_cbranch_vccnz .LBB0_227
	s_add_u32 s84, s0, 0x6000000
	s_addc_u32 s85, s1, 0
	s_add_u32 s52, s0, 0xd000000
	s_addc_u32 s53, s1, 0
	s_add_u32 s2, s0, 0xe000000
	v_writelane_b32 v255, s2, 17
	s_addc_u32 s2, s1, 0
	v_ashrrev_i32_e32 v17, 31, v16
	v_writelane_b32 v255, s2, 18
	v_lshl_add_u64 v[0:1], v[16:17], 4, s[0:1]
	s_mov_b64 s[2:3], 0x3d00000
	v_lshl_add_u64 v[18:19], v[0:1], 0, s[2:3]
	v_lshlrev_b32_e32 v93, 1, v16
	v_lshrrev_b32_e32 v1, 1, v16
	v_and_b32_e32 v0, 8, v93
	v_and_b32_e32 v1, 4, v1
	v_and_b32_e32 v5, -13, v16
	v_or3_b32 v0, v0, v5, v1
	v_ashrrev_i32_e32 v1, 31, v0
	v_lshl_add_u64 v[0:1], v[0:1], 1, s[0:1]
	s_mov_b64 s[2:3], 0xc000000
	v_and_b32_e32 v2, 31, v16
	s_waitcnt lgkmcnt(0)
	v_lshl_add_u64 v[20:21], v[0:1], 0, s[2:3]
	v_lshl_add_u64 v[0:1], v[16:17], 2, s[0:1]
	s_mov_b64 s[0:1], 0x3d80000
	v_lshrrev_b32_e32 v3, 5, v16
	v_lshl_add_u64 v[22:23], v[0:1], 0, s[0:1]
	v_bfe_u32 v1, v16, 6, 1
	v_lshlrev_b32_e32 v5, 9, v2
	v_and_b32_e32 v6, 15, v16
	v_bfe_u32 v4, v16, 5, 1
	v_cmp_eq_u32_e64 s[10:11], 0, v1
	v_lshl_or_b32 v94, v1, 14, v5
	v_lshl_or_b32 v1, v1, 5, v2
	v_bitop3_b32 v2, v3, v6, 1 bitop3:0x6c
	v_lshlrev_b32_e32 v95, 4, v2
	v_bitop3_b32 v2, v4, v6, 2 bitop3:0x36
	v_lshlrev_b32_e32 v96, 4, v2
	v_bitop3_b32 v2, v4, v6, 4 bitop3:0x36
	v_lshlrev_b32_e32 v97, 4, v2
	v_bitop3_b32 v2, v4, v6, 6 bitop3:0x36
	v_lshlrev_b32_e32 v98, 4, v2
	v_bitop3_b32 v2, v4, v6, 8 bitop3:0x36
	v_lshlrev_b32_e32 v99, 4, v2
	v_bitop3_b32 v2, v4, v6, 10 bitop3:0x36
	v_lshlrev_b32_e32 v100, 4, v2
	v_bitop3_b32 v2, v4, v6, 12 bitop3:0x36
	v_lshlrev_b32_e32 v101, 4, v2
	v_bitop3_b32 v2, v4, v6, 14 bitop3:0x36
	v_lshlrev_b32_e32 v102, 4, v2
	v_bitop3_b32 v2, v4, v6, 16 bitop3:0x36
	v_lshlrev_b32_e32 v103, 4, v2
	v_bitop3_b32 v2, v4, v6, 18 bitop3:0x36
	v_lshlrev_b32_e32 v104, 4, v2
	v_bitop3_b32 v2, v4, v6, 20 bitop3:0x36
	s_movk_i32 s0, 0x7f
	v_lshlrev_b32_e32 v105, 4, v2
	v_bitop3_b32 v2, v4, v6, 22 bitop3:0x36
	v_ashrrev_i32_e32 v0, 7, v16
	v_cmp_lt_u32_e32 vcc, s0, v16
	v_lshlrev_b32_e32 v106, 4, v2
	v_bitop3_b32 v2, v4, v6, 24 bitop3:0x36
	s_or_b64 s[0:1], vcc, s[10:11]
	v_lshl_or_b32 v17, v0, 14, v5
	v_lshlrev_b32_e32 v0, 5, v0
	v_lshlrev_b32_e32 v107, 4, v2
	v_bitop3_b32 v2, v4, v6, 26 bitop3:0x36
	v_writelane_b32 v255, s0, 19
	v_lshl_or_b32 v0, v4, 2, v0
	v_lshlrev_b32_e32 v108, 4, v2
	v_bitop3_b32 v2, v4, v6, 28 bitop3:0x36
	v_writelane_b32 v255, s1, 20
	v_cmp_gt_i32_e64 s[0:1], v1, v0
	v_lshlrev_b32_e32 v109, 4, v2
	v_bitop3_b32 v2, v4, v6, 30 bitop3:0x36
	v_writelane_b32 v255, s0, 21
	v_lshlrev_b32_e32 v110, 4, v2
	v_or_b32_e32 v2, 1, v0
	v_writelane_b32 v255, s1, 22
	v_cmp_gt_i32_e64 s[0:1], v1, v2
	v_lshl_or_b32 v26, v2, 6, v1
	v_or_b32_e32 v2, 2, v0
	v_writelane_b32 v255, s0, 23
	v_lshl_or_b32 v28, v2, 6, v1
	v_lshl_or_b32 v24, v0, 6, v1
	v_writelane_b32 v255, s1, 24
	v_cmp_gt_i32_e64 s[0:1], v1, v2
	v_or_b32_e32 v2, 3, v0
	v_lshl_or_b32 v30, v2, 6, v1
	v_writelane_b32 v255, s0, 25
	v_lshl_add_u32 v92, v16, 4, v235
	v_ashrrev_i32_e32 v25, 31, v24
	v_writelane_b32 v255, s1, 26
	v_cmp_gt_i32_e64 s[0:1], v1, v2
	v_or_b32_e32 v2, 8, v0
	v_lshl_or_b32 v32, v2, 6, v1
	v_writelane_b32 v255, s0, 27
	v_ashrrev_i32_e32 v27, 31, v26
	v_ashrrev_i32_e32 v29, 31, v28
	v_writelane_b32 v255, s1, 28
	v_cmp_gt_i32_e64 s[0:1], v1, v2
	v_or_b32_e32 v2, 9, v0
	v_lshl_or_b32 v34, v2, 6, v1
	v_writelane_b32 v255, s0, 29
	v_ashrrev_i32_e32 v31, 31, v30
	v_ashrrev_i32_e32 v33, 31, v32
	v_writelane_b32 v255, s1, 30
	v_cmp_gt_i32_e64 s[0:1], v1, v2
	v_or_b32_e32 v2, 10, v0
	v_cmp_gt_i32_e32 vcc, v1, v2
	v_lshl_or_b32 v36, v2, 6, v1
	v_or_b32_e32 v2, 11, v0
	v_cmp_gt_i32_e64 s[22:23], v1, v2
	v_lshl_or_b32 v38, v2, 6, v1
	v_or_b32_e32 v2, 16, v0
	v_cmp_gt_i32_e64 s[24:25], v1, v2
	v_lshl_or_b32 v40, v2, 6, v1
	v_or_b32_e32 v2, 17, v0
	v_cmp_gt_i32_e64 s[26:27], v1, v2
	v_lshl_or_b32 v42, v2, 6, v1
	v_or_b32_e32 v2, 18, v0
	v_cmp_gt_i32_e64 s[28:29], v1, v2
	v_lshl_or_b32 v44, v2, 6, v1
	v_or_b32_e32 v2, 19, v0
	v_cmp_gt_i32_e64 s[30:31], v1, v2
	v_lshl_or_b32 v46, v2, 6, v1
	v_or_b32_e32 v2, 24, v0
	v_cmp_gt_i32_e64 s[34:35], v1, v2
	v_lshl_or_b32 v48, v2, 6, v1
	v_or_b32_e32 v2, 25, v0
	v_cmp_gt_i32_e64 s[36:37], v1, v2
	v_lshl_or_b32 v50, v2, 6, v1
	v_or_b32_e32 v2, 26, v0
	v_or_b32_e32 v0, 27, v0
	v_writelane_b32 v255, s0, 31
	v_lshl_or_b32 v52, v2, 6, v1
	v_lshl_or_b32 v54, v0, 6, v1
	v_writelane_b32 v255, s1, 32
	v_ashrrev_i32_e32 v35, 31, v34
	v_ashrrev_i32_e32 v37, 31, v36
	v_ashrrev_i32_e32 v39, 31, v38
	v_ashrrev_i32_e32 v41, 31, v40
	v_ashrrev_i32_e32 v43, 31, v42
	v_ashrrev_i32_e32 v45, 31, v44
	v_ashrrev_i32_e32 v47, 31, v46
	v_ashrrev_i32_e32 v49, 31, v48
	v_ashrrev_i32_e32 v51, 31, v50
	v_cmp_gt_i32_e64 s[38:39], v1, v2
	v_ashrrev_i32_e32 v53, 31, v52
	v_cmp_gt_i32_e64 s[40:41], v1, v0
	v_ashrrev_i32_e32 v55, 31, v54
	v_xor_b32_e32 v111, 16, v93
	v_xor_b32_e32 v112, 32, v93
	v_xor_b32_e32 v113, 48, v93
	v_xor_b32_e32 v114, 64, v93
	v_xor_b32_e32 v115, 0x50, v93
	v_xor_b32_e32 v116, 0x60, v93
	v_xor_b32_e32 v117, 0x70, v93
	v_xor_b32_e32 v118, 0x80, v93
	v_xor_b32_e32 v119, 0x90, v93
	s_waitcnt vmcnt(9)
	v_xor_b32_e32 v120, 0xa0, v93
	v_xor_b32_e32 v121, 0xb0, v93
	v_xor_b32_e32 v122, 0xc0, v93
	v_xor_b32_e32 v123, 0xd0, v93
	s_waitcnt vmcnt(8)
	v_xor_b32_e32 v124, 0xe0, v93
	v_xor_b32_e32 v125, 0xf0, v93
	v_lshrrev_b32_e32 v2, 4, v1
	v_lshlrev_b32_e32 v2, 10, v2
	v_bfe_u32 v0, v1, 3, 1
	v_lshl_or_b32 v2, v0, 8, v2
	v_and_b32_e32 v0, 7, v1
	v_or_b32_e32 v2, v2, v0
	v_lshrrev_b32_e32 v0, 7, v16
	v_lshl_or_b32 v2, v0, 9, v2
	v_bfe_u32 v0, v16, 5, 1
	v_lshl_or_b32 v2, v0, 5, v2
	v_or_b32_e32 v24, 0, v2
	v_or_b32_e32 v26, 8, v2
	v_or_b32_e32 v28, 16, v2
	v_or_b32_e32 v30, 24, v2
	v_or_b32_e32 v32, 64, v2
	v_or_b32_e32 v34, 0x48, v2
	v_or_b32_e32 v36, 0x50, v2
	v_or_b32_e32 v38, 0x58, v2
	v_or_b32_e32 v40, 0x80, v2
	v_or_b32_e32 v42, 0x88, v2
	v_or_b32_e32 v44, 0x90, v2
	v_or_b32_e32 v46, 0x98, v2
	v_or_b32_e32 v48, 0xc0, v2
	v_or_b32_e32 v50, 0xc8, v2
	v_or_b32_e32 v52, 0xd0, v2
	v_or_b32_e32 v54, 0xd8, v2
	v_readlane_b32 s2, v254, 53
	v_readlane_b32 s3, v254, 54
	s_branch .LBB0_223
